# P3 attention loop: fewer VALU issue slots (SGPR-based K/V staging addresses, folded max/sum ops, packed scale-fma, lane-partial row sum combined at loop exit)
# speedup vs baseline: 1.0165x; 1.0056x over previous
.LBB0_432:
	s_ashr_i32 s69, s59, 6
	s_lshl_b32 s3, s59, 8
	s_lshl_b32 s2, s69, 11
	s_and_b32 s3, s3, 0x700
	s_bfe_u32 s6, s59, 0x10005
	s_or_b32 s26, s2, s3
	s_lshl_b32 s3, s59, 4
	s_ashr_i32 s27, s26, 31
	s_lshl_b32 s2, s6, 9
	s_and_b32 s3, s3, 0x180
	s_lshl_b32 s68, s6, 8
	s_or_b32 s63, s2, s3
	s_lshl_b64 s[2:3], s[26:27], 11
	s_add_u32 s2, s22, s2
	s_addc_u32 s3, s23, s3
	s_lshl_b32 s7, s63, 1
	s_add_u32 s8, s2, s7
	s_mul_i32 s2, s69, 0x1200
	s_addc_u32 s9, s3, 0
	s_mul_hi_i32 s3, s69, 0x1200
	s_or_b32 s2, s2, s6
	v_mov_b32_e32 v68, v208
	s_lshl_b64 s[6:7], s[2:3], 8
	s_add_u32 s2, s24, s6
	v_ashrrev_i32_e32 v16, 4, v68
	v_lshlrev_b32_e32 v22, 3, v68
	v_add_u32_e32 v18, 32, v16
	s_addc_u32 s3, s25, s7
	v_and_b32_e32 v0, 0x78, v22
	v_ashrrev_i32_e32 v17, 31, v16
	v_ashrrev_i32_e32 v19, 31, v18
	s_add_u32 s6, s1, s6
	v_lshlrev_b32_e32 v23, 1, v0
	v_lshlrev_b64 v[48:49], 9, v[16:17]
	v_lshlrev_b64 v[8:9], 9, v[18:19]
	s_addc_u32 s7, s54, s7
	v_or_b32_e32 v50, v48, v23
	v_mov_b32_e32 v51, v49
	v_or_b32_e32 v8, v8, v23
	v_ashrrev_i32_e32 v155, 6, v68
	v_lshl_add_u64 v[0:1], s[6:7], 0, v[50:51]
	v_lshl_add_u64 v[4:5], s[6:7], 0, v[8:9]
	v_lshl_add_u64 v[10:11], s[2:3], 0, v[50:51]
	v_lshl_add_u64 v[12:13], s[2:3], 0, v[8:9]
	v_and_b32_e32 v154, 31, v68
	v_lshlrev_b32_e32 v130, 5, v155
	global_load_dwordx4 v[0:3], v[0:1], off
	s_nop 0
	global_load_dwordx4 v[4:7], v[4:5], off
	s_nop 0
	global_load_dwordx4 v[8:11], v[10:11], off
	s_nop 0
	global_load_dwordx4 v[12:15], v[12:13], off
	v_or_b32_e32 v20, v130, v154
	v_ashrrev_i32_e32 v21, 31, v20
	v_bfe_u32 v153, v68, 5, 1
	v_lshlrev_b64 v[20:21], 11, v[20:21]
	v_lshl_add_u64 v[20:21], s[8:9], 0, v[20:21]
	v_lshlrev_b32_e32 v128, 4, v153
	v_lshl_add_u64 v[20:21], v[20:21], 0, v[128:129]
	global_load_dwordx4 v[124:127], v[20:21], off
	global_load_dwordx4 v[120:123], v[20:21], off offset:32
	global_load_dwordx4 v[112:115], v[20:21], off offset:64
	global_load_dwordx4 v[116:119], v[20:21], off offset:96
	global_load_dwordx4 v[108:111], v[20:21], off offset:128
	global_load_dwordx4 v[104:107], v[20:21], off offset:160
	global_load_dwordx4 v[100:103], v[20:21], off offset:192
	global_load_dwordx4 v[96:99], v[20:21], off offset:224
	v_and_b32_e32 v19, 0xfffff0, v16
	v_lshlrev_b32_e32 v24, 1, v16
	v_lshrrev_b32_e32 v25, 1, v16
	v_and_b32_e32 v26, 3, v16
	v_and_or_b32 v19, v24, 8, v19
	v_and_or_b32 v24, v25, 4, v26
	v_and_b32_e32 v25, 0xfffff0, v18
	v_lshlrev_b32_e32 v26, 1, v18
	v_and_b32_e32 v17, 0x70, v68
	v_bfe_u32 v22, v22, 5, 2
	v_lshlrev_b32_e32 v16, 8, v16
	v_lshlrev_b32_e32 v18, 8, v18
	v_lshrrev_b32_e32 v19, 1, v19
	v_and_or_b32 v25, v26, 8, v25
	v_lshlrev_b32_e32 v156, 4, v68
	v_bitop3_b32 v162, v23, v16, v17 bitop3:0xde
	v_bitop3_b32 v163, v23, v18, v17 bitop3:0xde
	v_or_b32_e32 v16, v19, v22
	v_lshrrev_b32_e32 v17, 1, v25
	v_lshlrev_b32_e32 v24, 6, v24
	v_and_b32_e32 v27, 48, v23
	v_lshlrev_b32_e32 v16, 9, v16
	v_or_b32_e32 v17, v17, v22
	v_lshlrev_b32_e32 v60, 8, v154
	v_and_b32_e32 v61, 0x70, v156
	v_or3_b32 v164, v16, v24, v27
	v_lshlrev_b32_e32 v16, 9, v17
	v_bitop3_b32 v166, v128, v60, v61 bitop3:0xde
	v_or3_b32 v165, v16, v24, v27
	s_waitcnt vmcnt(0)
	v_and_b32_e32 v62, 0x3fffffc0, v68
	v_and_b32_e32 v157, 63, v68
	v_lshlrev_b32_e32 v63, 1, v68
	v_lshl_add_u32 v131, v62, 2, v150
	v_lshlrev_b32_e32 v62, 3, v157
	v_lshl_or_b32 v158, v154, 2, v131
	s_waitcnt vmcnt(11)
	ds_write_b128 v164, v[0:3]
	s_waitcnt vmcnt(10)
	ds_write_b128 v165, v[4:7]
	s_waitcnt vmcnt(9)
	ds_write_b128 v162, v[8:11] offset:32768
	s_waitcnt vmcnt(8)
	ds_write_b128 v163, v[12:15] offset:32768
	s_waitcnt lgkmcnt(0)
	s_barrier
	ds_read_b128 v[0:3], v166 offset:32768
	ds_read_b128 v[4:7], v166 offset:40960
	s_waitcnt vmcnt(7) lgkmcnt(1)
	v_mfma_f32_32x32x16_bf16 v[32:47], v[0:3], v[124:127], 0
	v_or_b32_e32 v0, 32, v128
	v_bitop3_b32 v167, v0, v60, v61 bitop3:0xde
	v_mov_b32_e32 v159, 0
	s_waitcnt lgkmcnt(0)
	v_mfma_f32_32x32x16_bf16 v[16:31], v[4:7], v[124:127], 0
	ds_read_b128 v[0:3], v167 offset:32768
	ds_read_b128 v[4:7], v167 offset:40960
	s_waitcnt vmcnt(6) lgkmcnt(1)
	v_mfma_f32_32x32x16_bf16 v[32:47], v[0:3], v[120:123], v[32:47]
	v_or_b32_e32 v0, 64, v128
	v_bitop3_b32 v168, v0, v60, v61 bitop3:0xde
	s_waitcnt lgkmcnt(0)
	v_mfma_f32_32x32x16_bf16 v[16:31], v[4:7], v[120:123], v[16:31]
	ds_read_b128 v[0:3], v168 offset:32768
	ds_read_b128 v[4:7], v168 offset:40960
	s_waitcnt vmcnt(5) lgkmcnt(1)
	v_mfma_f32_32x32x16_bf16 v[32:47], v[0:3], v[112:115], v[32:47]
	v_or_b32_e32 v0, 0x60, v128
	v_bitop3_b32 v169, v0, v60, v61 bitop3:0xde
	s_waitcnt lgkmcnt(0)
	v_mfma_f32_32x32x16_bf16 v[16:31], v[4:7], v[112:115], v[16:31]
	ds_read_b128 v[0:3], v169 offset:32768
	ds_read_b128 v[4:7], v169 offset:40960
	s_waitcnt vmcnt(4) lgkmcnt(1)
	v_mfma_f32_32x32x16_bf16 v[32:47], v[0:3], v[116:119], v[32:47]
	v_or_b32_e32 v0, 0x80, v128
	v_bitop3_b32 v170, v0, v60, v61 bitop3:0xde
	s_waitcnt lgkmcnt(0)
	v_mfma_f32_32x32x16_bf16 v[16:31], v[4:7], v[116:119], v[16:31]
	ds_read_b128 v[0:3], v170 offset:32768
	ds_read_b128 v[4:7], v170 offset:40960
	s_waitcnt vmcnt(3) lgkmcnt(1)
	v_mfma_f32_32x32x16_bf16 v[32:47], v[0:3], v[108:111], v[32:47]
	v_or_b32_e32 v0, 0xa0, v128
	v_bitop3_b32 v171, v0, v60, v61 bitop3:0xde
	s_waitcnt lgkmcnt(0)
	v_mfma_f32_32x32x16_bf16 v[16:31], v[4:7], v[108:111], v[16:31]
	ds_read_b128 v[0:3], v171 offset:32768
	ds_read_b128 v[4:7], v171 offset:40960
	s_waitcnt vmcnt(2) lgkmcnt(1)
	v_mfma_f32_32x32x16_bf16 v[32:47], v[0:3], v[104:107], v[32:47]
	v_or_b32_e32 v0, 0xc0, v128
	v_bitop3_b32 v172, v0, v60, v61 bitop3:0xde
	ds_read_b128 v[52:55], v172 offset:32768
	ds_read_b128 v[56:59], v172 offset:40960
	s_waitcnt lgkmcnt(2)
	v_mfma_f32_32x32x16_bf16 v[16:31], v[4:7], v[104:107], v[16:31]
	v_mov_b64_e32 v[0:1], s[36:37]
	v_mov_b64_e32 v[14:15], s[50:51]
	v_mov_b64_e32 v[2:3], s[38:39]
	v_mov_b64_e32 v[4:5], s[40:41]
	v_mov_b64_e32 v[6:7], s[42:43]
	v_mov_b64_e32 v[8:9], s[44:45]
	v_mov_b64_e32 v[10:11], s[46:47]
	s_waitcnt vmcnt(1) lgkmcnt(1)
	v_mfma_f32_32x32x16_bf16 v[32:47], v[52:55], v[100:103], v[32:47]
	v_or_b32_e32 v52, 0xe0, v128
	v_bitop3_b32 v173, v52, v60, v61 bitop3:0xde
	ds_read_b128 v[52:55], v173 offset:32768
	v_lshl_add_u64 v[60:61], v[50:51], 0, s[16:17]
	v_lshl_add_u64 v[50:51], v[50:51], 0, s[18:19]
	v_lshl_add_u64 v[64:65], s[2:3], 0, v[50:51]
	v_mov_b64_e32 v[12:13], s[48:49]
	s_waitcnt lgkmcnt(1)
	v_mfma_f32_32x32x16_bf16 v[16:31], v[56:59], v[100:103], v[16:31]
	v_and_b32_e32 v56, 0xc0, v156
	v_and_b32_e32 v57, 32, v63
	v_and_or_b32 v56, v62, 24, v56
	v_and_b32_e32 v58, 0x100, v62
	v_or3_b32 v161, v56, v57, v58
	ds_read_b128 v[56:59], v173 offset:40960
	v_or_b32_e32 v160, 0x4000, v161
	s_waitcnt vmcnt(0) lgkmcnt(1)
	v_mfma_f32_32x32x16_bf16 v[32:47], v[52:55], v[96:99], v[32:47]
	v_lshl_add_u64 v[54:55], s[2:3], 0, v[60:61]
	v_lshl_add_u64 v[52:53], s[6:7], 0, v[60:61]
	v_lshl_add_u64 v[60:61], s[6:7], 0, v[50:51]
	global_load_dwordx4 v[50:53], v[52:53], off
	s_nop 0
	global_load_dwordx4 v[60:63], v[60:61], off
	v_cmp_gt_u32_e64 s[6:7], 32, v157
	s_waitcnt lgkmcnt(0)
	v_mfma_f32_32x32x16_bf16 v[16:31], v[56:59], v[96:99], v[16:31]
	global_load_dwordx4 v[54:57], v[54:55], off
	s_nop 0
	global_load_dwordx4 v[64:67], v[64:65], off
	v_max_f32_e32 v58, v33, v33
	v_max_f32_e32 v59, v32, v32
	v_max_f32_e32 v58, v59, v58
	v_max3_f32 v58, v58, v34, v35
	v_max3_f32 v58, v58, v36, v37
	v_max3_f32 v58, v58, v38, v39
	v_max3_f32 v58, v58, v40, v41
	v_max3_f32 v58, v58, v42, v43
	v_max3_f32 v58, v58, v44, v45
	v_max3_f32 v58, v58, v46, v47
	v_max3_f32 v58, v58, v16, v17
	v_max3_f32 v58, v58, v18, v19
	v_max3_f32 v58, v58, v20, v21
	v_max3_f32 v58, v58, v22, v23
	v_max3_f32 v58, v58, v24, v25
	v_max3_f32 v58, v58, v26, v27
	v_max3_f32 v58, v58, v28, v29
	v_max3_f32 v58, v58, v30, v31
	v_mov_b32_e32 v59, v58
	s_nop 1
	v_permlane32_swap_b32_e32 v58, v59
	v_max_f32_e32 v59, v59, v59
	v_max_f32_e32 v58, v58, v58
	v_max_f32_e32 v58, v58, v59
	v_add_f32_e32 v59, 0x7149f2ca, v58
	v_max_f32_e32 v58, 0xf149f2ca, v58
	v_cmp_ge_f32_e32 vcc, s15, v59
	v_sub_f32_e32 v59, 0xf149f2ca, v58
	v_mul_f32_e32 v59, 0x3e0293ee, v59
	v_exp_f32_e32 v59, v59
	s_cmp_eq_u64 vcc, exec
	s_cselect_b64 vcc, -1, 0
	v_cndmask_b32_e32 v175, v58, v151, vcc
	v_mul_f32_e32 v58, 0xbe0293ee, v175
	v_cndmask_b32_e64 v174, v59, 1.0, vcc
	v_mov_b32_e32 v59, v58
	v_fmac_f32_e32 v59, 0x3e0293ee, v47
	v_fmamk_f32 v32, v32, 0x3e0293ee, v58
	v_fmamk_f32 v33, v33, 0x3e0293ee, v58
	v_fmamk_f32 v34, v34, 0x3e0293ee, v58
	v_fmamk_f32 v35, v35, 0x3e0293ee, v58
	v_fmamk_f32 v36, v36, 0x3e0293ee, v58
	v_fmamk_f32 v37, v37, 0x3e0293ee, v58
	v_fmamk_f32 v38, v38, 0x3e0293ee, v58
	v_fmamk_f32 v39, v39, 0x3e0293ee, v58
	v_fmamk_f32 v40, v40, 0x3e0293ee, v58
	v_fmamk_f32 v41, v41, 0x3e0293ee, v58
	v_fmamk_f32 v42, v42, 0x3e0293ee, v58
	v_fmamk_f32 v43, v43, 0x3e0293ee, v58
	v_fmamk_f32 v44, v44, 0x3e0293ee, v58
	v_fmamk_f32 v45, v45, 0x3e0293ee, v58
	v_fmamk_f32 v46, v46, 0x3e0293ee, v58
	v_pk_fma_f32 v[140:141], v[18:19], s[14:15], v[58:59] op_sel_hi:[1,0,0]
	v_and_b32_e32 v18, 15, v68
	v_pk_fma_f32 v[142:143], v[16:17], s[14:15], v[58:59] op_sel_hi:[1,0,0]
	v_exp_f32_e32 v190, v32
	v_exp_f32_e32 v191, v33
	v_exp_f32_e32 v192, v34
	v_exp_f32_e32 v193, v35
	v_exp_f32_e32 v194, v36
	v_exp_f32_e32 v196, v37
	v_exp_f32_e32 v195, v38
	v_exp_f32_e32 v197, v39
	v_exp_f32_e32 v182, v40
	v_exp_f32_e32 v183, v41
	v_exp_f32_e32 v184, v42
	v_exp_f32_e32 v186, v43
	v_exp_f32_e32 v185, v44
	v_exp_f32_e32 v187, v45
	v_exp_f32_e32 v188, v46
	v_exp_f32_e32 v189, v59
	v_mad_i64_i32 v[16:17], s[2:3], s69, v152, v[48:49]
	v_lshlrev_b32_e32 v18, 4, v18
	s_waitcnt vmcnt(0)
	v_or3_b32 v16, v16, s68, v18
	v_pk_fma_f32 v[144:145], v[30:31], s[14:15], v[58:59] op_sel_hi:[1,0,0]
	v_pk_fma_f32 v[146:147], v[28:29], s[14:15], v[58:59] op_sel_hi:[1,0,0]
	v_pk_fma_f32 v[148:149], v[26:27], s[14:15], v[58:59] op_sel_hi:[1,0,0]
	v_pk_fma_f32 v[134:135], v[24:25], s[14:15], v[58:59] op_sel_hi:[1,0,0]
	v_pk_fma_f32 v[136:137], v[22:23], s[14:15], v[58:59] op_sel_hi:[1,0,0]
	v_pk_fma_f32 v[138:139], v[20:21], s[14:15], v[58:59] op_sel_hi:[1,0,0]
	s_waitcnt vmcnt(3)
	ds_write_b128 v164, v[50:53] offset:16384
	s_waitcnt vmcnt(2)
	ds_write_b128 v165, v[60:63] offset:16384
	s_waitcnt vmcnt(1)
	ds_write_b128 v162, v[54:57] offset:49152
	s_waitcnt vmcnt(0)
	ds_write_b128 v163, v[64:67] offset:49152
	v_lshl_add_u64 v[132:133], s[12:13], 0, v[16:17]
	v_mov_b64_e32 v[62:63], v[14:15]
	v_mov_b64_e32 v[46:47], v[14:15]
	v_mov_b64_e32 v[30:31], v[14:15]
	s_mov_b32 s68, -1
	v_mov_b64_e32 v[60:61], v[12:13]
	v_mov_b64_e32 v[58:59], v[10:11]
	v_mov_b64_e32 v[56:57], v[8:9]
	v_mov_b64_e32 v[54:55], v[6:7]
	v_mov_b64_e32 v[52:53], v[4:5]
	v_mov_b64_e32 v[50:51], v[2:3]
	v_mov_b64_e32 v[48:49], v[0:1]
	v_mov_b64_e32 v[44:45], v[12:13]
	v_mov_b64_e32 v[42:43], v[10:11]
	v_mov_b64_e32 v[40:41], v[8:9]
	v_mov_b64_e32 v[38:39], v[6:7]
	v_mov_b64_e32 v[36:37], v[4:5]
	v_mov_b64_e32 v[34:35], v[2:3]
	v_mov_b64_e32 v[32:33], v[0:1]
	v_mov_b64_e32 v[28:29], v[12:13]
	v_mov_b64_e32 v[26:27], v[10:11]
	v_mov_b64_e32 v[24:25], v[8:9]
	v_mov_b64_e32 v[22:23], v[6:7]
	v_mov_b64_e32 v[20:21], v[4:5]
	v_mov_b64_e32 v[18:19], v[2:3]
	v_mov_b64_e32 v[16:17], v[0:1]
	s_waitcnt lgkmcnt(0)
	s_barrier
	v_readfirstlane_b32 s28, v132
	v_readfirstlane_b32 s29, v133
	s_nop 1
	v_subrev_u32_e32 v132, s28, v132
	v_add_u32_e32 v133, 0x4000, v132
	s_sub_u32 s30, s28, 0x120c000
	s_subb_u32 s31, s29, 0
	s_sub_u32 s28, s28, 0xc000
	s_subb_u32 s29, s29, 0
.LBB0_433:
	ds_read_b128 v[64:67], v166 offset:49152
	ds_read_b128 v[68:71], v166 offset:57344
	ds_read_b128 v[176:179], v167 offset:49152
	ds_read_b128 v[198:201], v167 offset:57344
	ds_read_b128 v[202:205], v168 offset:49152
	ds_read_b128 v[210:213], v168 offset:57344
	v_exp_f32_e32 v142, v142
	v_exp_f32_e32 v143, v143
	s_waitcnt lgkmcnt(5)
	v_mfma_f32_32x32x16_bf16 v[80:95], v[64:67], v[124:127], 0
	v_exp_f32_e32 v180, v140
	v_exp_f32_e32 v181, v141
	v_exp_f32_e32 v206, v138
	v_exp_f32_e32 v207, v135
	v_exp_f32_e32 v148, v148
	v_exp_f32_e32 v149, v149
	v_exp_f32_e32 v209, v146
	s_waitcnt lgkmcnt(4)
	v_mfma_f32_32x32x16_bf16 v[64:79], v[68:71], v[124:127], 0
	v_cvt_pk_bf16_f32 v135, v192, v193
	v_cvt_pk_bf16_f32 v138, v182, v183
	v_cvt_pk_bf16_f32 v140, v185, v187
	v_cvt_pk_bf16_f32 v141, v188, v189
	s_nop 0
	v_permlane32_swap_b32_e32 v138, v140
	s_waitcnt lgkmcnt(3)
	v_mfma_f32_32x32x16_bf16 v[80:95], v[176:179], v[120:123], v[80:95]
	ds_read_b128 v[176:179], v169 offset:49152
	ds_read_b128 v[214:217], v169 offset:57344
	ds_read_b128 v[218:221], v170 offset:49152
	ds_read_b128 v[222:225], v170 offset:57344
	ds_read_b128 v[226:229], v171 offset:49152
	ds_read_b128 v[230:233], v171 offset:57344
	ds_read_b128 v[234:237], v172 offset:49152
	ds_read_b128 v[238:241], v172 offset:57344
	s_waitcnt lgkmcnt(10)
	v_mfma_f32_32x32x16_bf16 v[64:79], v[198:201], v[120:123], v[64:79]
	ds_read_b128 v[198:201], v173 offset:49152
	ds_read_b128 v[242:245], v173 offset:57344
	s_waitcnt lgkmcnt(11)
	v_mfma_f32_32x32x16_bf16 v[80:95], v[202:205], v[112:115], v[80:95]
	v_exp_f32_e32 v205, v134
	v_add_f32_e32 v134, v191, v190
	v_add_f32_e32 v134, v192, v134
	v_add_f32_e32 v134, v193, v134
	v_add_f32_e32 v134, v194, v134
	v_add_f32_e32 v134, v196, v134
	s_waitcnt lgkmcnt(10)
	v_mfma_f32_32x32x16_bf16 v[64:79], v[210:213], v[112:115], v[64:79]
	v_add_f32_e32 v134, v195, v134
	v_add_f32_e32 v134, v197, v134
	v_add_f32_e32 v134, v182, v134
	v_add_f32_e32 v134, v183, v134
	v_add_f32_e32 v134, v184, v134
	v_add_f32_e32 v134, v186, v134
	v_add_f32_e32 v134, v185, v134
	s_waitcnt lgkmcnt(9)
	v_mfma_f32_32x32x16_bf16 v[80:95], v[176:179], v[116:119], v[80:95]
	v_add_f32_e32 v134, v187, v134
	v_add_f32_e32 v134, v188, v134
	v_add_f32_e32 v134, v189, v134
	v_add_f32_e32 v134, v142, v134
	v_exp_f32_e32 v202, v139
	v_add_f32_e32 v134, v143, v134
	v_exp_f32_e32 v203, v136
	s_waitcnt lgkmcnt(8)
	v_mfma_f32_32x32x16_bf16 v[64:79], v[214:217], v[116:119], v[64:79]
	v_add_f32_e32 v134, v180, v134
	v_exp_f32_e32 v204, v137
	v_add_f32_e32 v134, v181, v134
	v_add_f32_e32 v134, v206, v134
	v_add_f32_e32 v134, v202, v134
	v_add_f32_e32 v134, v203, v134
	v_add_f32_e32 v134, v204, v134
	s_waitcnt lgkmcnt(7)
	v_mfma_f32_32x32x16_bf16 v[80:95], v[218:221], v[108:111], v[80:95]
	v_add_f32_e32 v134, v205, v134
	v_exp_f32_e32 v210, v147
	v_add_f32_e32 v134, v207, v134
	v_exp_f32_e32 v211, v144
	v_add_f32_e32 v134, v148, v134
	v_exp_f32_e32 v212, v145
	v_add_f32_e32 v134, v149, v134
	s_waitcnt lgkmcnt(6)
	v_mfma_f32_32x32x16_bf16 v[64:79], v[222:225], v[108:111], v[64:79]
	v_add_f32_e32 v134, v209, v134
	v_add_f32_e32 v134, v210, v134
	v_add_f32_e32 v134, v211, v134
	v_add_f32_e32 v176, v212, v134
	v_cvt_pk_bf16_f32 v134, v190, v191
	v_cvt_pk_bf16_f32 v136, v194, v196
	s_waitcnt lgkmcnt(5)
	v_mfma_f32_32x32x16_bf16 v[80:95], v[226:229], v[104:107], v[80:95]
	v_cvt_pk_bf16_f32 v137, v195, v197
	v_permlane32_swap_b32_e32 v134, v136
	v_cvt_pk_bf16_f32 v139, v184, v186
	v_cvt_pk_bf16_f32 v142, v142, v143
	s_waitcnt lgkmcnt(4)
	v_mfma_f32_32x32x16_bf16 v[64:79], v[230:233], v[104:107], v[64:79]
	v_cvt_pk_bf16_f32 v143, v180, v181
	v_cvt_pk_bf16_f32 v144, v206, v202
	v_cvt_pk_bf16_f32 v145, v203, v204
	v_cvt_pk_bf16_f32 v146, v205, v207
	v_cvt_pk_bf16_f32 v147, v148, v149
	v_cvt_pk_bf16_f32 v148, v209, v210
	v_cvt_pk_bf16_f32 v149, v211, v212
	s_waitcnt lgkmcnt(3)
	v_mfma_f32_32x32x16_bf16 v[80:95], v[234:237], v[100:103], v[80:95]
	v_permlane32_swap_b32_e32 v135, v137
	v_permlane32_swap_b32_e32 v139, v141
	v_permlane32_swap_b32_e32 v142, v144
	v_permlane32_swap_b32_e32 v143, v145
	s_waitcnt lgkmcnt(2)
	v_mfma_f32_32x32x16_bf16 v[64:79], v[238:241], v[100:103], v[64:79]
	v_permlane32_swap_b32_e32 v146, v148
	v_permlane32_swap_b32_e32 v147, v149
	s_waitcnt lgkmcnt(1)
	v_mfma_f32_32x32x16_bf16 v[80:95], v[198:201], v[96:99], v[80:95]
	s_waitcnt lgkmcnt(0)
	v_mfma_f32_32x32x16_bf16 v[64:79], v[242:245], v[96:99], v[64:79]
	global_load_dwordx4 v[180:183], v132, s[28:29]
	global_load_dwordx4 v[184:187], v133, s[28:29]
	global_load_dwordx4 v[188:191], v132, s[30:31]
	global_load_dwordx4 v[192:195], v133, s[30:31]
	s_add_u32 s28, s28, 0x8000
	s_addc_u32 s29, s29, 0
	s_add_u32 s30, s30, 0x8000
	s_addc_u32 s31, s31, 0
	ds_read_b64_tr_b16 v[196:197], v161 offset:0
	ds_read_b64_tr_b16 v[198:199], v161 offset:0x800
	ds_read_b64_tr_b16 v[200:201], v161 offset:0x1000
	ds_read_b64_tr_b16 v[202:203], v161 offset:0x1800
	ds_read_b64_tr_b16 v[204:205], v161 offset:0x2000
	ds_read_b64_tr_b16 v[206:207], v161 offset:0x2800
	ds_read_b64_tr_b16 v[210:211], v161 offset:0x3000
	ds_read_b64_tr_b16 v[212:213], v161 offset:0x3800
	s_waitcnt lgkmcnt(0)
	s_nop 0
	v_mfma_f32_32x32x16_bf16 v[0:15], v[134:137], v[196:199], v[0:15]
	ds_read_b64_tr_b16 v[196:197], v161 offset:0x200
	ds_read_b64_tr_b16 v[198:199], v161 offset:0xa00
	v_mfma_f32_32x32x16_bf16 v[0:15], v[138:141], v[200:203], v[0:15]
	ds_read_b64_tr_b16 v[200:201], v161 offset:0x1200
	ds_read_b64_tr_b16 v[202:203], v161 offset:0x1a00
	v_mfma_f32_32x32x16_bf16 v[0:15], v[142:145], v[204:207], v[0:15]
	ds_read_b64_tr_b16 v[204:205], v161 offset:0x2200
	ds_read_b64_tr_b16 v[206:207], v161 offset:0x2a00
	ds_read_b64_tr_b16 v[214:215], v161 offset:0x3200
	ds_read_b64_tr_b16 v[216:217], v161 offset:0x3a00
	s_waitcnt lgkmcnt(0)
	v_mfma_f32_32x32x16_bf16 v[0:15], v[146:149], v[210:213], v[0:15]
	v_mfma_f32_32x32x16_bf16 v[48:63], v[134:137], v[196:199], v[48:63]
	ds_read_b64_tr_b16 v[196:197], v161 offset:0x400
	ds_read_b64_tr_b16 v[198:199], v161 offset:0xc00
	v_mfma_f32_32x32x16_bf16 v[48:63], v[138:141], v[200:203], v[48:63]
	ds_read_b64_tr_b16 v[200:201], v161 offset:0x1400
	ds_read_b64_tr_b16 v[202:203], v161 offset:0x1c00
	v_mfma_f32_32x32x16_bf16 v[48:63], v[142:145], v[204:207], v[48:63]
	ds_read_b64_tr_b16 v[204:205], v161 offset:0x2400
	ds_read_b64_tr_b16 v[206:207], v161 offset:0x2c00
	ds_read_b64_tr_b16 v[210:211], v161 offset:0x3400
	ds_read_b64_tr_b16 v[212:213], v161 offset:0x3c00
	s_waitcnt lgkmcnt(0)
	v_mfma_f32_32x32x16_bf16 v[48:63], v[146:149], v[214:217], v[48:63]
	v_mfma_f32_32x32x16_bf16 v[32:47], v[134:137], v[196:199], v[32:47]
	ds_read_b64_tr_b16 v[196:197], v161 offset:0x600
	ds_read_b64_tr_b16 v[198:199], v161 offset:0xe00
	v_mfma_f32_32x32x16_bf16 v[32:47], v[138:141], v[200:203], v[32:47]
	ds_read_b64_tr_b16 v[200:201], v161 offset:0x1600
	ds_read_b64_tr_b16 v[202:203], v161 offset:0x1e00
	v_mfma_f32_32x32x16_bf16 v[32:47], v[142:145], v[204:207], v[32:47]
	ds_read_b64_tr_b16 v[204:205], v161 offset:0x2600
	ds_read_b64_tr_b16 v[206:207], v161 offset:0x2e00
	ds_read_b64_tr_b16 v[214:215], v161 offset:0x3600
	ds_read_b64_tr_b16 v[216:217], v161 offset:0x3e00
	s_waitcnt lgkmcnt(0)
	v_mfma_f32_32x32x16_bf16 v[32:47], v[146:149], v[210:213], v[32:47]
	v_mfma_f32_32x32x16_bf16 v[16:31], v[134:137], v[196:199], v[16:31]
	v_max_f32_e32 v177, v80, v81
	v_max3_f32 v177, v177, v82, v83
	v_max3_f32 v177, v177, v84, v85
	v_max3_f32 v134, v177, v86, v87
	v_max3_f32 v134, v134, v88, v89
	v_max3_f32 v134, v134, v90, v91
	v_mfma_f32_32x32x16_bf16 v[16:31], v[138:141], v[200:203], v[16:31]
	v_max3_f32 v134, v134, v92, v93
	v_max3_f32 v134, v134, v94, v95
	v_max3_f32 v134, v134, v64, v65
	v_max3_f32 v134, v134, v66, v67
	v_max3_f32 v134, v134, v68, v69
	v_max3_f32 v134, v134, v70, v71
	v_max3_f32 v134, v134, v72, v73
	v_max3_f32 v134, v134, v74, v75
	v_mfma_f32_32x32x16_bf16 v[16:31], v[142:145], v[204:207], v[16:31]
	v_max3_f32 v134, v134, v76, v77
	v_max3_f32 v134, v134, v78, v79
	v_mov_b32_e32 v135, v134
	s_nop 1
	v_permlane32_swap_b32_e32 v134, v135
	v_max_f32_e32 v134, v134, v135
	v_sub_f32_e32 v135, v134, v175
	v_max_f32_e32 v134, v175, v134
	v_mfma_f32_32x32x16_bf16 v[16:31], v[146:149], v[214:217], v[16:31]
	v_sub_f32_e32 v136, v175, v134
	v_mul_f32_e32 v136, 0x3e0293ee, v136
	v_exp_f32_e32 v136, v136
	v_cmp_ge_f32_e32 vcc, s15, v135
	s_cmp_eq_u64 vcc, exec
	s_cselect_b64 s[8:9], -1, 0
	s_barrier
	s_waitcnt vmcnt(0)
	v_cndmask_b32_e64 v179, v136, 1.0, s[8:9]
	v_cmp_gt_f32_e32 vcc, 1.0, v179
	s_waitcnt vmcnt(3)
	ds_write_b128 v164, v[180:183]
	s_waitcnt vmcnt(2)
	ds_write_b128 v165, v[184:187]
	s_waitcnt vmcnt(1)
	ds_write_b128 v162, v[188:191] offset:32768
	s_waitcnt vmcnt(0)
	ds_write_b128 v163, v[192:195] offset:32768
	s_cbranch_vccz .LBB0_437
	s_and_saveexec_b64 s[2:3], s[6:7]
	ds_write_b32 v158, v179 offset:128
	s_or_b64 exec, exec, s[2:3]
	s_waitcnt lgkmcnt(0)
	v_add_u32_e32 v135, v131, v128
	ds_read_b128 v[136:139], v135 offset:224
	ds_read_b128 v[140:143], v135 offset:192
	ds_read_b128 v[144:147], v135 offset:160
	ds_read_b128 v[180:183], v135 offset:128
	s_waitcnt lgkmcnt(3)
	v_pk_mul_f32 v[12:13], v[12:13], v[136:137]
	s_waitcnt lgkmcnt(2)
	v_pk_mul_f32 v[8:9], v[8:9], v[140:141]
	s_waitcnt lgkmcnt(1)
	v_pk_mul_f32 v[4:5], v[4:5], v[144:145]
	v_pk_mul_f32 v[14:15], v[14:15], v[138:139]
	v_pk_mul_f32 v[10:11], v[10:11], v[142:143]
	v_pk_mul_f32 v[6:7], v[6:7], v[146:147]
	s_waitcnt lgkmcnt(0)
	v_pk_mul_f32 v[2:3], v[2:3], v[182:183]
	v_pk_mul_f32 v[0:1], v[0:1], v[180:181]
	v_pk_mul_f32 v[60:61], v[60:61], v[136:137]
	v_pk_mul_f32 v[56:57], v[56:57], v[140:141]
	v_pk_mul_f32 v[52:53], v[52:53], v[144:145]
	v_pk_mul_f32 v[62:63], v[62:63], v[138:139]
	v_pk_mul_f32 v[58:59], v[58:59], v[142:143]
	v_pk_mul_f32 v[54:55], v[54:55], v[146:147]
	v_pk_mul_f32 v[50:51], v[50:51], v[182:183]
	v_pk_mul_f32 v[48:49], v[48:49], v[180:181]
	v_pk_mul_f32 v[44:45], v[44:45], v[136:137]
	v_pk_mul_f32 v[40:41], v[40:41], v[140:141]
	v_pk_mul_f32 v[36:37], v[36:37], v[144:145]
	v_pk_mul_f32 v[46:47], v[46:47], v[138:139]
	v_pk_mul_f32 v[42:43], v[42:43], v[142:143]
	v_pk_mul_f32 v[38:39], v[38:39], v[146:147]
	v_pk_mul_f32 v[34:35], v[34:35], v[182:183]
	v_pk_mul_f32 v[32:33], v[32:33], v[180:181]
	v_pk_mul_f32 v[28:29], v[28:29], v[136:137]
	v_pk_mul_f32 v[24:25], v[24:25], v[140:141]
	v_pk_mul_f32 v[20:21], v[20:21], v[144:145]
	v_pk_mul_f32 v[30:31], v[30:31], v[138:139]
	v_pk_mul_f32 v[26:27], v[26:27], v[142:143]
	v_pk_mul_f32 v[22:23], v[22:23], v[146:147]
	v_pk_mul_f32 v[18:19], v[18:19], v[182:183]
	v_pk_mul_f32 v[16:17], v[16:17], v[180:181]
.LBB0_437:
	v_cndmask_b32_e64 v134, v134, v175, s[8:9]
	v_mul_f32_e32 v196, 0xbe0293ee, v134
	v_pk_fma_f32 v[88:89], v[88:89], s[14:15], v[196:197] op_sel_hi:[1,0,0]
	v_pk_fma_f32 v[80:81], v[80:81], s[14:15], v[196:197] op_sel_hi:[1,0,0]
	v_pk_fma_f32 v[82:83], v[82:83], s[14:15], v[196:197] op_sel_hi:[1,0,0]
	v_pk_fma_f32 v[84:85], v[84:85], s[14:15], v[196:197] op_sel_hi:[1,0,0]
	v_pk_fma_f32 v[86:87], v[86:87], s[14:15], v[196:197] op_sel_hi:[1,0,0]
	v_pk_fma_f32 v[90:91], v[90:91], s[14:15], v[196:197] op_sel_hi:[1,0,0]
	v_pk_fma_f32 v[92:93], v[92:93], s[14:15], v[196:197] op_sel_hi:[1,0,0]
	v_pk_fma_f32 v[94:95], v[94:95], s[14:15], v[196:197] op_sel_hi:[1,0,0]
	v_exp_f32_e32 v135, v88
	v_pk_fma_f32 v[188:189], v[64:65], s[14:15], v[196:197] op_sel_hi:[1,0,0]
	v_pk_fma_f32 v[190:191], v[66:67], s[14:15], v[196:197] op_sel_hi:[1,0,0]
	v_fmamk_f32 v192, v68, 0x3e0293ee, v196
	v_fmamk_f32 v181, v69, 0x3e0293ee, v196
	v_pk_fma_f32 v[182:183], v[70:71], s[14:15], v[196:197] op_sel_hi:[1,0,0]
	v_pk_fma_f32 v[184:185], v[72:73], s[14:15], v[196:197] op_sel_hi:[1,0,0]
	v_pk_fma_f32 v[186:187], v[74:75], s[14:15], v[196:197] op_sel_hi:[1,0,0]
	v_fmamk_f32 v180, v76, 0x3e0293ee, v196
	v_fmamk_f32 v193, v77, 0x3e0293ee, v196
	v_fmamk_f32 v194, v78, 0x3e0293ee, v196
	v_fmamk_f32 v177, v79, 0x3e0293ee, v196
	v_exp_f32_e32 v143, v80
	v_exp_f32_e32 v144, v81
	v_exp_f32_e32 v145, v82
	v_exp_f32_e32 v146, v83
	v_exp_f32_e32 v147, v84
	v_exp_f32_e32 v149, v85
	v_exp_f32_e32 v148, v86
	v_exp_f32_e32 v175, v87
	v_exp_f32_e32 v136, v89
	v_exp_f32_e32 v137, v90
	v_exp_f32_e32 v139, v91
	v_exp_f32_e32 v138, v92
	v_exp_f32_e32 v140, v93
	v_exp_f32_e32 v141, v94
	v_exp_f32_e32 v142, v95
	s_waitcnt lgkmcnt(0)
	s_barrier
	ds_read_b128 v[64:67], v166 offset:32768
	ds_read_b128 v[68:71], v166 offset:40960
	ds_read_b128 v[196:199], v167 offset:32768
	ds_read_b128 v[200:203], v167 offset:40960
	ds_read_b128 v[204:207], v168 offset:32768
	ds_read_b128 v[210:213], v168 offset:40960
	v_exp_f32_e32 v188, v188
	v_exp_f32_e32 v189, v189
	s_waitcnt lgkmcnt(5)
	v_mfma_f32_32x32x16_bf16 v[80:95], v[64:67], v[124:127], 0
	v_exp_f32_e32 v190, v190
	v_exp_f32_e32 v191, v191
	v_exp_f32_e32 v192, v192
	v_exp_f32_e32 v195, v181
	v_exp_f32_e32 v182, v182
	v_exp_f32_e32 v183, v183
	v_exp_f32_e32 v184, v184
	s_waitcnt lgkmcnt(4)
	v_mfma_f32_32x32x16_bf16 v[64:79], v[68:71], v[124:127], 0
	v_exp_f32_e32 v185, v185
	v_exp_f32_e32 v186, v186
	v_exp_f32_e32 v187, v187
	v_exp_f32_e32 v193, v193
	v_exp_f32_e32 v194, v194
	v_exp_f32_e32 v177, v177
	s_waitcnt lgkmcnt(3)
	v_mfma_f32_32x32x16_bf16 v[80:95], v[196:199], v[120:123], v[80:95]
	ds_read_b128 v[196:199], v169 offset:32768
	ds_read_b128 v[214:217], v169 offset:40960
	ds_read_b128 v[218:221], v170 offset:32768
	ds_read_b128 v[222:225], v170 offset:40960
	ds_read_b128 v[226:229], v171 offset:32768
	ds_read_b128 v[230:233], v171 offset:40960
	ds_read_b128 v[234:237], v172 offset:32768
	ds_read_b128 v[238:241], v172 offset:40960
	s_waitcnt lgkmcnt(10)
	v_mfma_f32_32x32x16_bf16 v[64:79], v[200:203], v[120:123], v[64:79]
	ds_read_b128 v[200:203], v173 offset:32768
	ds_read_b128 v[242:245], v173 offset:40960
	s_waitcnt lgkmcnt(11)
	v_mfma_f32_32x32x16_bf16 v[80:95], v[204:207], v[112:115], v[80:95]
	v_exp_f32_e32 v204, v180
	v_add_f32_e32 v180, v144, v143
	v_add_f32_e32 v180, v145, v180
	v_add_f32_e32 v180, v146, v180
	v_add_f32_e32 v180, v147, v180
	v_add_f32_e32 v180, v149, v180
	s_waitcnt lgkmcnt(10)
	v_mfma_f32_32x32x16_bf16 v[64:79], v[210:213], v[112:115], v[64:79]
	v_add_f32_e32 v180, v148, v180
	v_add_f32_e32 v180, v175, v180
	v_add_f32_e32 v180, v135, v180
	v_add_f32_e32 v180, v136, v180
	v_add_f32_e32 v180, v137, v180
	v_add_f32_e32 v180, v139, v180
	v_add_f32_e32 v180, v138, v180
	s_waitcnt lgkmcnt(9)
	v_mfma_f32_32x32x16_bf16 v[80:95], v[196:199], v[116:119], v[80:95]
	v_add_f32_e32 v180, v140, v180
	v_add_f32_e32 v180, v141, v180
	v_add_f32_e32 v180, v142, v180
	v_add_f32_e32 v180, v188, v180
	v_add_f32_e32 v180, v189, v180
	v_add_f32_e32 v180, v190, v180
	v_add_f32_e32 v180, v191, v180
	s_waitcnt lgkmcnt(8)
	v_mfma_f32_32x32x16_bf16 v[64:79], v[214:217], v[116:119], v[64:79]
	v_add_f32_e32 v180, v192, v180
	v_add_f32_e32 v180, v195, v180
	v_add_f32_e32 v180, v182, v180
	v_add_f32_e32 v180, v183, v180
	v_add_f32_e32 v180, v184, v180
	v_add_f32_e32 v180, v185, v180
	v_add_f32_e32 v180, v186, v180
	s_waitcnt lgkmcnt(7)
	v_mfma_f32_32x32x16_bf16 v[80:95], v[218:221], v[108:111], v[80:95]
	v_add_f32_e32 v180, v187, v180
	v_add_f32_e32 v180, v204, v180
	v_add_f32_e32 v180, v193, v180
	v_add_f32_e32 v180, v194, v180
	v_add_f32_e32 v180, v177, v180
	s_waitcnt lgkmcnt(6)
	v_mfma_f32_32x32x16_bf16 v[64:79], v[222:225], v[108:111], v[64:79]
	v_cvt_pk_bf16_f32 v144, v143, v144
	v_cvt_pk_bf16_f32 v145, v145, v146
	v_cvt_pk_bf16_f32 v146, v147, v149
	v_cvt_pk_bf16_f32 v147, v148, v175
	v_cvt_pk_bf16_f32 v136, v135, v136
	v_cvt_pk_bf16_f32 v137, v137, v139
	v_cvt_pk_bf16_f32 v138, v138, v140
	s_waitcnt lgkmcnt(5)
	v_mfma_f32_32x32x16_bf16 v[80:95], v[226:229], v[104:107], v[80:95]
	v_cvt_pk_bf16_f32 v139, v141, v142
	v_cvt_pk_bf16_f32 v140, v188, v189
	v_cvt_pk_bf16_f32 v141, v190, v191
	v_cvt_pk_bf16_f32 v142, v192, v195
	v_cvt_pk_bf16_f32 v143, v182, v183
	v_cvt_pk_bf16_f32 v182, v184, v185
	v_cvt_pk_bf16_f32 v183, v186, v187
	s_waitcnt lgkmcnt(4)
	v_mfma_f32_32x32x16_bf16 v[64:79], v[230:233], v[104:107], v[64:79]
	v_cvt_pk_bf16_f32 v184, v204, v193
	v_cvt_pk_bf16_f32 v185, v194, v177
	v_permlane32_swap_b32_e32 v144, v146
	v_permlane32_swap_b32_e32 v145, v147
	v_permlane32_swap_b32_e32 v136, v138
	s_waitcnt lgkmcnt(3)
	v_mfma_f32_32x32x16_bf16 v[80:95], v[234:237], v[100:103], v[80:95]
	v_permlane32_swap_b32_e32 v137, v139
	v_permlane32_swap_b32_e32 v140, v142
	v_permlane32_swap_b32_e32 v141, v143
	v_permlane32_swap_b32_e32 v182, v184
	s_waitcnt lgkmcnt(2)
	v_mfma_f32_32x32x16_bf16 v[64:79], v[238:241], v[100:103], v[64:79]
	v_permlane32_swap_b32_e32 v183, v185
	s_waitcnt lgkmcnt(1)
	v_mfma_f32_32x32x16_bf16 v[80:95], v[200:203], v[96:99], v[80:95]
	s_waitcnt lgkmcnt(0)
	v_mfma_f32_32x32x16_bf16 v[64:79], v[242:245], v[96:99], v[64:79]
	global_load_dwordx4 v[186:189], v132, s[28:29]
	global_load_dwordx4 v[190:193], v132, s[30:31]
	global_load_dwordx4 v[194:197], v133, s[28:29]
	global_load_dwordx4 v[198:201], v133, s[30:31]
	s_add_u32 s28, s28, 0x8000
	s_addc_u32 s29, s29, 0
	s_add_u32 s30, s30, 0x8000
	s_addc_u32 s31, s31, 0
	ds_read_b64_tr_b16 v[202:203], v160 offset:0
	ds_read_b64_tr_b16 v[204:205], v160 offset:0x800
	ds_read_b64_tr_b16 v[210:211], v160 offset:0x1000
	ds_read_b64_tr_b16 v[212:213], v160 offset:0x1800
	ds_read_b64_tr_b16 v[214:215], v160 offset:0x2000
	ds_read_b64_tr_b16 v[216:217], v160 offset:0x2800
	ds_read_b64_tr_b16 v[218:219], v160 offset:0x3000
	ds_read_b64_tr_b16 v[220:221], v160 offset:0x3800
	s_waitcnt lgkmcnt(0)
	s_nop 0
	v_mfma_f32_32x32x16_bf16 v[0:15], v[144:147], v[202:205], v[0:15]
	ds_read_b64_tr_b16 v[202:203], v160 offset:0x200
	ds_read_b64_tr_b16 v[204:205], v160 offset:0xa00
	v_mfma_f32_32x32x16_bf16 v[0:15], v[136:139], v[210:213], v[0:15]
	ds_read_b64_tr_b16 v[210:211], v160 offset:0x1200
	ds_read_b64_tr_b16 v[212:213], v160 offset:0x1a00
	v_mfma_f32_32x32x16_bf16 v[0:15], v[140:143], v[214:217], v[0:15]
	ds_read_b64_tr_b16 v[214:215], v160 offset:0x2200
	ds_read_b64_tr_b16 v[216:217], v160 offset:0x2a00
	ds_read_b64_tr_b16 v[222:223], v160 offset:0x3200
	ds_read_b64_tr_b16 v[224:225], v160 offset:0x3a00
	s_waitcnt lgkmcnt(0)
	v_mfma_f32_32x32x16_bf16 v[0:15], v[182:185], v[218:221], v[0:15]
	v_mfma_f32_32x32x16_bf16 v[48:63], v[144:147], v[202:205], v[48:63]
	ds_read_b64_tr_b16 v[202:203], v160 offset:0x400
	ds_read_b64_tr_b16 v[204:205], v160 offset:0xc00
	v_mfma_f32_32x32x16_bf16 v[48:63], v[136:139], v[210:213], v[48:63]
	ds_read_b64_tr_b16 v[210:211], v160 offset:0x1400
	ds_read_b64_tr_b16 v[212:213], v160 offset:0x1c00
	v_mfma_f32_32x32x16_bf16 v[48:63], v[140:143], v[214:217], v[48:63]
	ds_read_b64_tr_b16 v[214:215], v160 offset:0x2400
	ds_read_b64_tr_b16 v[216:217], v160 offset:0x2c00
	ds_read_b64_tr_b16 v[218:219], v160 offset:0x3400
	ds_read_b64_tr_b16 v[220:221], v160 offset:0x3c00
	s_waitcnt lgkmcnt(0)
	v_mfma_f32_32x32x16_bf16 v[48:63], v[182:185], v[222:225], v[48:63]
	v_mfma_f32_32x32x16_bf16 v[32:47], v[144:147], v[202:205], v[32:47]
	ds_read_b64_tr_b16 v[202:203], v160 offset:0x600
	ds_read_b64_tr_b16 v[204:205], v160 offset:0xe00
	v_mfma_f32_32x32x16_bf16 v[32:47], v[136:139], v[210:213], v[32:47]
	ds_read_b64_tr_b16 v[210:211], v160 offset:0x1600
	ds_read_b64_tr_b16 v[212:213], v160 offset:0x1e00
	v_mfma_f32_32x32x16_bf16 v[32:47], v[140:143], v[214:217], v[32:47]
	ds_read_b64_tr_b16 v[214:215], v160 offset:0x2600
	ds_read_b64_tr_b16 v[216:217], v160 offset:0x2e00
	ds_read_b64_tr_b16 v[222:223], v160 offset:0x3600
	ds_read_b64_tr_b16 v[224:225], v160 offset:0x3e00
	s_waitcnt lgkmcnt(0)
	v_mfma_f32_32x32x16_bf16 v[32:47], v[182:185], v[218:221], v[32:47]
	v_mfma_f32_32x32x16_bf16 v[16:31], v[144:147], v[202:205], v[16:31]
	v_max_f32_e32 v135, v80, v81
	v_max3_f32 v135, v135, v82, v83
	v_max3_f32 v135, v135, v84, v85
	v_max3_f32 v135, v135, v86, v87
	v_max3_f32 v135, v135, v88, v89
	v_max3_f32 v135, v135, v90, v91
	v_mfma_f32_32x32x16_bf16 v[16:31], v[136:139], v[210:213], v[16:31]
	v_max3_f32 v135, v135, v92, v93
	v_max3_f32 v135, v135, v94, v95
	v_max3_f32 v135, v135, v64, v65
	v_max3_f32 v135, v135, v66, v67
	v_max3_f32 v135, v135, v68, v69
	v_max3_f32 v135, v135, v70, v71
	v_max3_f32 v135, v135, v72, v73
	v_max3_f32 v135, v135, v74, v75
	v_mfma_f32_32x32x16_bf16 v[16:31], v[140:143], v[214:217], v[16:31]
	v_max3_f32 v135, v135, v76, v77
	v_max3_f32 v135, v135, v78, v79
	v_mov_b32_e32 v136, v135
	s_nop 1
	v_permlane32_swap_b32_e32 v135, v136
	v_max_f32_e32 v135, v135, v136
	v_sub_f32_e32 v136, v135, v134
	v_max_f32_e32 v135, v134, v135
	v_mfma_f32_32x32x16_bf16 v[16:31], v[182:185], v[222:225], v[16:31]
	v_sub_f32_e32 v137, v134, v135
	v_mul_f32_e32 v137, 0x3e0293ee, v137
	v_exp_f32_e32 v137, v137
	v_cmp_ge_f32_e32 vcc, s15, v136
	s_cmp_eq_u64 vcc, exec
	s_cselect_b64 s[8:9], -1, 0
	s_barrier
	s_waitcnt vmcnt(0)
	v_cndmask_b32_e64 v177, v137, 1.0, s[8:9]
	v_cmp_gt_f32_e32 vcc, 1.0, v177
	s_waitcnt vmcnt(3)
	ds_write_b128 v164, v[186:189] offset:16384
	s_waitcnt vmcnt(1)
	ds_write_b128 v165, v[194:197] offset:16384
	ds_write_b128 v162, v[190:193] offset:49152
	s_waitcnt vmcnt(0)
	ds_write_b128 v163, v[198:201] offset:49152
	s_cbranch_vccz .LBB0_441
	s_and_saveexec_b64 s[2:3], s[6:7]
	ds_write_b32 v158, v177 offset:128
	s_or_b64 exec, exec, s[2:3]
	s_waitcnt lgkmcnt(0)
	v_add_u32_e32 v148, v131, v128
	ds_read_b128 v[136:139], v148 offset:224
	ds_read_b128 v[140:143], v148 offset:192
	ds_read_b128 v[144:147], v148 offset:160
	ds_read_b128 v[182:185], v148 offset:128
	s_waitcnt lgkmcnt(3)
	v_pk_mul_f32 v[12:13], v[12:13], v[136:137]
	s_waitcnt lgkmcnt(2)
	v_pk_mul_f32 v[8:9], v[8:9], v[140:141]
	s_waitcnt lgkmcnt(1)
	v_pk_mul_f32 v[4:5], v[4:5], v[144:145]
	v_pk_mul_f32 v[14:15], v[14:15], v[138:139]
	v_pk_mul_f32 v[10:11], v[10:11], v[142:143]
	v_pk_mul_f32 v[6:7], v[6:7], v[146:147]
	s_waitcnt lgkmcnt(0)
	v_pk_mul_f32 v[2:3], v[2:3], v[184:185]
	v_pk_mul_f32 v[0:1], v[0:1], v[182:183]
	v_pk_mul_f32 v[60:61], v[60:61], v[136:137]
	v_pk_mul_f32 v[56:57], v[56:57], v[140:141]
	v_pk_mul_f32 v[52:53], v[52:53], v[144:145]
	v_pk_mul_f32 v[62:63], v[62:63], v[138:139]
	v_pk_mul_f32 v[58:59], v[58:59], v[142:143]
	v_pk_mul_f32 v[54:55], v[54:55], v[146:147]
	v_pk_mul_f32 v[50:51], v[50:51], v[184:185]
	v_pk_mul_f32 v[48:49], v[48:49], v[182:183]
	v_pk_mul_f32 v[44:45], v[44:45], v[136:137]
	v_pk_mul_f32 v[40:41], v[40:41], v[140:141]
	v_pk_mul_f32 v[36:37], v[36:37], v[144:145]
	v_pk_mul_f32 v[46:47], v[46:47], v[138:139]
	v_pk_mul_f32 v[42:43], v[42:43], v[142:143]
	v_pk_mul_f32 v[38:39], v[38:39], v[146:147]
	v_pk_mul_f32 v[34:35], v[34:35], v[184:185]
	v_pk_mul_f32 v[32:33], v[32:33], v[182:183]
	v_pk_mul_f32 v[28:29], v[28:29], v[136:137]
	v_pk_mul_f32 v[24:25], v[24:25], v[140:141]
	v_pk_mul_f32 v[20:21], v[20:21], v[144:145]
	v_pk_mul_f32 v[30:31], v[30:31], v[138:139]
	v_pk_mul_f32 v[26:27], v[26:27], v[142:143]
	v_pk_mul_f32 v[22:23], v[22:23], v[146:147]
	v_pk_mul_f32 v[18:19], v[18:19], v[184:185]
	v_pk_mul_f32 v[16:17], v[16:17], v[182:183]
.LBB0_441:
	v_cndmask_b32_e64 v175, v135, v134, s[8:9]
	v_mul_f32_e32 v144, 0xbe0293ee, v175
	v_pk_fma_f32 v[80:81], v[80:81], s[14:15], v[144:145] op_sel_hi:[1,0,0]
	v_pk_fma_f32 v[82:83], v[82:83], s[14:15], v[144:145] op_sel_hi:[1,0,0]
	v_pk_fma_f32 v[84:85], v[84:85], s[14:15], v[144:145] op_sel_hi:[1,0,0]
	v_pk_fma_f32 v[86:87], v[86:87], s[14:15], v[144:145] op_sel_hi:[1,0,0]
	v_pk_fma_f32 v[88:89], v[88:89], s[14:15], v[144:145] op_sel_hi:[1,0,0]
	v_pk_fma_f32 v[90:91], v[90:91], s[14:15], v[144:145] op_sel_hi:[1,0,0]
	v_pk_fma_f32 v[92:93], v[92:93], s[14:15], v[144:145] op_sel_hi:[1,0,0]
	v_fmamk_f32 v94, v94, 0x3e0293ee, v144
	v_fmamk_f32 v145, v95, 0x3e0293ee, v144
	v_exp_f32_e32 v190, v80
	v_exp_f32_e32 v191, v81
	v_exp_f32_e32 v192, v82
	v_exp_f32_e32 v193, v83
	v_exp_f32_e32 v194, v84
	v_exp_f32_e32 v196, v85
	v_exp_f32_e32 v195, v86
	v_exp_f32_e32 v197, v87
	v_exp_f32_e32 v182, v88
	v_exp_f32_e32 v183, v89
	v_exp_f32_e32 v184, v90
	v_exp_f32_e32 v186, v91
	v_exp_f32_e32 v185, v92
	v_exp_f32_e32 v187, v93
	v_exp_f32_e32 v188, v94
	v_exp_f32_e32 v189, v145
	v_pk_fma_f32 v[142:143], v[64:65], s[14:15], v[144:145] op_sel_hi:[1,0,0]
	v_fma_f32 v64, v174, v159, v176
	s_add_i32 s68, s68, 2
	v_pk_fma_f32 v[140:141], v[66:67], s[14:15], v[144:145] op_sel_hi:[1,0,0]
	v_pk_fma_f32 v[138:139], v[68:69], s[14:15], v[144:145] op_sel_hi:[1,0,0]
	v_pk_fma_f32 v[136:137], v[70:71], s[14:15], v[144:145] op_sel_hi:[1,0,0]
	v_pk_fma_f32 v[134:135], v[72:73], s[14:15], v[144:145] op_sel_hi:[1,0,0]
	v_pk_fma_f32 v[148:149], v[74:75], s[14:15], v[144:145] op_sel_hi:[1,0,0]
	v_pk_fma_f32 v[146:147], v[76:77], s[14:15], v[144:145] op_sel_hi:[1,0,0]
	v_pk_fma_f32 v[144:145], v[78:79], s[14:15], v[144:145] op_sel_hi:[1,0,0]
	v_fma_f32 v159, v64, v179, v180
	s_cmp_gt_u32 s68, 32
	s_waitcnt lgkmcnt(0)
	s_barrier
	s_cbranch_scc1 .LBB0_443
	v_mov_b32_e32 v174, v177
	s_branch .LBB0_433
.LBB0_443:
	v_mov_b32_e32 v178, v159
	s_nop 1
	v_permlane32_swap_b32_e32 v159, v178
	v_add_f32_e32 v159, v159, v178
	ds_read_b128 v[64:67], v166 offset:49152
	ds_read_b128 v[68:71], v166 offset:57344
	v_exp_f32_e32 v132, v142
	v_exp_f32_e32 v133, v143
	v_exp_f32_e32 v140, v140
	s_waitcnt lgkmcnt(1)
	v_mfma_f32_32x32x16_bf16 v[80:95], v[64:67], v[124:127], 0
	v_exp_f32_e32 v141, v141
	v_exp_f32_e32 v138, v138
	v_exp_f32_e32 v139, v139
	v_exp_f32_e32 v136, v136
	v_exp_f32_e32 v137, v137
	v_exp_f32_e32 v134, v134
	v_exp_f32_e32 v135, v135
	s_waitcnt lgkmcnt(0)
	v_mfma_f32_32x32x16_bf16 v[64:79], v[68:71], v[124:127], 0
	ds_read_b128 v[124:127], v167 offset:49152
	ds_read_b128 v[162:165], v167 offset:57344
	ds_read_b128 v[178:181], v168 offset:49152
	ds_read_b128 v[198:201], v168 offset:57344
	v_exp_f32_e32 v142, v148
	v_exp_f32_e32 v143, v149
	v_exp_f32_e32 v146, v146
	v_exp_f32_e32 v147, v147
	v_exp_f32_e32 v144, v144
	v_exp_f32_e32 v145, v145
	s_waitcnt lgkmcnt(3)
	v_mfma_f32_32x32x16_bf16 v[80:95], v[124:127], v[120:123], v[80:95]
	ds_read_b128 v[124:127], v169 offset:49152
	ds_read_b128 v[166:169], v169 offset:57344
	ds_read_b128 v[202:205], v170 offset:49152
	ds_read_b128 v[210:213], v170 offset:57344
	ds_read_b128 v[214:217], v171 offset:49152
	ds_read_b128 v[218:221], v171 offset:57344
	ds_read_b128 v[222:225], v172 offset:49152
	ds_read_b128 v[226:229], v172 offset:57344
	s_waitcnt lgkmcnt(10)
	v_mfma_f32_32x32x16_bf16 v[64:79], v[162:165], v[120:123], v[64:79]
	ds_read_b128 v[120:123], v173 offset:49152
	ds_read_b128 v[162:165], v173 offset:57344
	s_waitcnt lgkmcnt(11)
	v_mfma_f32_32x32x16_bf16 v[80:95], v[178:181], v[112:115], v[80:95]
	s_waitcnt lgkmcnt(10)
	v_mfma_f32_32x32x16_bf16 v[64:79], v[198:201], v[112:115], v[64:79]
	v_add_f32_e32 v112, 0, v190
	v_add_f32_e32 v112, v191, v112
	v_add_f32_e32 v112, v192, v112
	v_add_f32_e32 v112, v193, v112
	v_add_f32_e32 v112, v194, v112
	v_add_f32_e32 v112, v196, v112
	v_add_f32_e32 v112, v195, v112
	s_waitcnt lgkmcnt(9)
	v_mfma_f32_32x32x16_bf16 v[80:95], v[124:127], v[116:119], v[80:95]
	v_add_f32_e32 v112, v197, v112
	v_add_f32_e32 v112, v182, v112
	v_add_f32_e32 v112, v183, v112
	v_add_f32_e32 v112, v184, v112
	v_add_f32_e32 v112, v186, v112
	v_add_f32_e32 v112, v185, v112
	v_add_f32_e32 v112, v187, v112
	s_waitcnt lgkmcnt(8)
	v_mfma_f32_32x32x16_bf16 v[64:79], v[166:169], v[116:119], v[64:79]
	v_add_f32_e32 v112, v188, v112
	v_add_f32_e32 v112, v189, v112
	v_add_f32_e32 v112, v132, v112
	v_add_f32_e32 v112, v133, v112
	v_add_f32_e32 v112, v140, v112
	v_add_f32_e32 v112, v141, v112
	v_add_f32_e32 v112, v138, v112
	s_waitcnt lgkmcnt(7)
	v_mfma_f32_32x32x16_bf16 v[80:95], v[202:205], v[108:111], v[80:95]
	v_add_f32_e32 v112, v139, v112
	v_add_f32_e32 v112, v136, v112
	v_add_f32_e32 v112, v137, v112
	v_cvt_pk_bf16_f32 v113, v195, v197
	v_cvt_pk_bf16_f32 v114, v132, v133
	v_cvt_pk_bf16_f32 v115, v140, v141
	v_cvt_pk_bf16_f32 v116, v138, v139
	s_waitcnt lgkmcnt(6)
	v_mfma_f32_32x32x16_bf16 v[64:79], v[210:213], v[108:111], v[64:79]
	v_add_f32_e32 v108, v134, v112
	v_add_f32_e32 v108, v135, v108
	v_add_f32_e32 v108, v142, v108
	v_add_f32_e32 v108, v143, v108
	v_add_f32_e32 v108, v146, v108
	v_add_f32_e32 v108, v147, v108
	v_add_f32_e32 v108, v144, v108
	s_waitcnt lgkmcnt(5)
	v_mfma_f32_32x32x16_bf16 v[80:95], v[214:217], v[104:107], v[80:95]
	v_add_f32_e32 v108, v145, v108
	v_mov_b32_e32 v109, v108
	s_nop 1
	v_permlane32_swap_b32_e32 v108, v109
	v_cvt_pk_bf16_f32 v110, v190, v191
	v_cvt_pk_bf16_f32 v111, v192, v193
	v_cvt_pk_bf16_f32 v112, v194, v196
	s_waitcnt lgkmcnt(4)
	v_mfma_f32_32x32x16_bf16 v[64:79], v[218:221], v[104:107], v[64:79]
	v_cvt_pk_bf16_f32 v104, v182, v183
	v_cvt_pk_bf16_f32 v105, v184, v186
	v_cvt_pk_bf16_f32 v106, v185, v187
	v_cvt_pk_bf16_f32 v107, v188, v189
	v_cvt_pk_bf16_f32 v117, v136, v137
	v_permlane32_swap_b32_e32 v110, v112
	s_waitcnt lgkmcnt(3)
	v_mfma_f32_32x32x16_bf16 v[80:95], v[222:225], v[100:103], v[80:95]
	v_permlane32_swap_b32_e32 v111, v113
	v_permlane32_swap_b32_e32 v104, v106
	v_permlane32_swap_b32_e32 v105, v107
	v_permlane32_swap_b32_e32 v114, v116
	s_waitcnt lgkmcnt(2)
	v_mfma_f32_32x32x16_bf16 v[64:79], v[226:229], v[100:103], v[64:79]
	v_cvt_pk_bf16_f32 v100, v134, v135
	v_cvt_pk_bf16_f32 v101, v142, v143
	v_cvt_pk_bf16_f32 v102, v146, v147
	v_cvt_pk_bf16_f32 v103, v144, v145
	v_permlane32_swap_b32_e32 v115, v117
	v_permlane32_swap_b32_e32 v100, v102
	s_waitcnt lgkmcnt(1)
	v_mfma_f32_32x32x16_bf16 v[80:95], v[120:123], v[96:99], v[80:95]
	v_permlane32_swap_b32_e32 v101, v103
	s_waitcnt lgkmcnt(0)
	v_mfma_f32_32x32x16_bf16 v[64:79], v[162:165], v[96:99], v[64:79]
	ds_read_b64_tr_b16 v[96:97], v161 offset:0
	ds_read_b64_tr_b16 v[98:99], v161 offset:0x800
	ds_read_b64_tr_b16 v[118:119], v161 offset:0x1000
	ds_read_b64_tr_b16 v[120:121], v161 offset:0x1800
	ds_read_b64_tr_b16 v[122:123], v161 offset:0x2000
	ds_read_b64_tr_b16 v[124:125], v161 offset:0x2800
	ds_read_b64_tr_b16 v[132:133], v161 offset:0x3000
	ds_read_b64_tr_b16 v[134:135], v161 offset:0x3800
	s_waitcnt lgkmcnt(0)
	s_nop 0
	v_mfma_f32_32x32x16_bf16 v[0:15], v[110:113], v[96:99], v[0:15]
	ds_read_b64_tr_b16 v[96:97], v161 offset:0x200
	ds_read_b64_tr_b16 v[98:99], v161 offset:0xa00
	v_mfma_f32_32x32x16_bf16 v[0:15], v[104:107], v[118:121], v[0:15]
	ds_read_b64_tr_b16 v[118:119], v161 offset:0x1200
	ds_read_b64_tr_b16 v[120:121], v161 offset:0x1a00
	v_mfma_f32_32x32x16_bf16 v[0:15], v[114:117], v[122:125], v[0:15]
	ds_read_b64_tr_b16 v[122:123], v161 offset:0x2200
	ds_read_b64_tr_b16 v[124:125], v161 offset:0x2a00
	ds_read_b64_tr_b16 v[136:137], v161 offset:0x3200
	ds_read_b64_tr_b16 v[138:139], v161 offset:0x3a00
	s_waitcnt lgkmcnt(0)
	v_mfma_f32_32x32x16_bf16 v[0:15], v[100:103], v[132:135], v[0:15]
	v_mfma_f32_32x32x16_bf16 v[48:63], v[110:113], v[96:99], v[48:63]
	ds_read_b64_tr_b16 v[96:97], v161 offset:0x400
	ds_read_b64_tr_b16 v[98:99], v161 offset:0xc00
	v_mfma_f32_32x32x16_bf16 v[48:63], v[104:107], v[118:121], v[48:63]
	ds_read_b64_tr_b16 v[118:119], v161 offset:0x1400
	ds_read_b64_tr_b16 v[120:121], v161 offset:0x1c00
	v_mfma_f32_32x32x16_bf16 v[48:63], v[114:117], v[122:125], v[48:63]
	ds_read_b64_tr_b16 v[122:123], v161 offset:0x2400
	ds_read_b64_tr_b16 v[124:125], v161 offset:0x2c00
	ds_read_b64_tr_b16 v[132:133], v161 offset:0x3400
	ds_read_b64_tr_b16 v[134:135], v161 offset:0x3c00
	s_waitcnt lgkmcnt(0)
	v_mfma_f32_32x32x16_bf16 v[48:63], v[100:103], v[136:139], v[48:63]
	v_mfma_f32_32x32x16_bf16 v[32:47], v[110:113], v[96:99], v[32:47]
	ds_read_b64_tr_b16 v[96:97], v161 offset:0x600
	ds_read_b64_tr_b16 v[98:99], v161 offset:0xe00
	v_mfma_f32_32x32x16_bf16 v[32:47], v[104:107], v[118:121], v[32:47]
	ds_read_b64_tr_b16 v[118:119], v161 offset:0x1600
	ds_read_b64_tr_b16 v[120:121], v161 offset:0x1e00
	v_mfma_f32_32x32x16_bf16 v[32:47], v[114:117], v[122:125], v[32:47]
	ds_read_b64_tr_b16 v[122:123], v161 offset:0x2600
	ds_read_b64_tr_b16 v[124:125], v161 offset:0x2e00
	ds_read_b64_tr_b16 v[136:137], v161 offset:0x3600
	ds_read_b64_tr_b16 v[138:139], v161 offset:0x3e00
	s_waitcnt lgkmcnt(0)
	v_mfma_f32_32x32x16_bf16 v[32:47], v[100:103], v[132:135], v[32:47]
	v_mfma_f32_32x32x16_bf16 v[16:31], v[110:113], v[96:99], v[16:31]
	v_max_f32_e32 v126, v81, v81
	v_max_f32_e32 v127, v80, v80
	v_max_f32_e32 v126, v127, v126
	v_max3_f32 v126, v126, v82, v83
	v_max3_f32 v126, v126, v84, v85
	v_max3_f32 v96, v126, v86, v87
	v_max3_f32 v96, v96, v88, v89
	v_max3_f32 v96, v96, v90, v91
	v_mfma_f32_32x32x16_bf16 v[16:31], v[104:107], v[118:121], v[16:31]
	v_max3_f32 v96, v96, v92, v93
	v_max3_f32 v96, v96, v94, v95
	v_max3_f32 v96, v96, v64, v65
	v_max3_f32 v96, v96, v66, v67
	v_max3_f32 v96, v96, v68, v69
	v_max3_f32 v96, v96, v70, v71
	v_max3_f32 v96, v96, v72, v73
	v_max3_f32 v96, v96, v74, v75
	v_mfma_f32_32x32x16_bf16 v[16:31], v[114:117], v[122:125], v[16:31]
	v_max3_f32 v96, v96, v76, v77
	v_max3_f32 v96, v96, v78, v79
	v_mov_b32_e32 v97, v96
	s_nop 1
	v_permlane32_swap_b32_e32 v96, v97
	v_max_f32_e32 v97, v97, v97
	v_max_f32_e32 v96, v96, v96
	v_max_f32_e32 v96, v96, v97
	v_max_f32_e32 v97, v175, v175
	v_max_f32_e32 v97, v97, v96
	v_sub_f32_e32 v98, v96, v175
	v_mfma_f32_32x32x16_bf16 v[16:31], v[100:103], v[136:139], v[16:31]
	v_sub_f32_e32 v96, v175, v97
	v_mul_f32_e32 v96, 0x3e0293ee, v96
	v_exp_f32_e32 v96, v96
	v_cmp_ge_f32_e32 vcc, s15, v98
	s_cmp_eq_u64 vcc, exec
	s_cselect_b64 s[8:9], -1, 0
	v_cndmask_b32_e64 v96, v96, 1.0, s[8:9]
	v_cmp_gt_f32_e32 vcc, 1.0, v96
	s_barrier
	s_cbranch_vccz .LBB0_447
	s_and_saveexec_b64 s[2:3], s[6:7]
	ds_write_b32 v158, v96 offset:128
	s_or_b64 exec, exec, s[2:3]
	s_waitcnt lgkmcnt(0)
	v_add_u32_e32 v106, v131, v128
	ds_read_b128 v[98:101], v106 offset:224
	ds_read_b128 v[102:105], v106 offset:192
	ds_read_b128 v[110:113], v106 offset:160
	ds_read_b128 v[114:117], v106 offset:128
	s_waitcnt lgkmcnt(3)
	v_pk_mul_f32 v[12:13], v[12:13], v[98:99]
	s_waitcnt lgkmcnt(2)
	v_pk_mul_f32 v[8:9], v[8:9], v[102:103]
	s_waitcnt lgkmcnt(1)
	v_pk_mul_f32 v[4:5], v[4:5], v[110:111]
	v_pk_mul_f32 v[14:15], v[14:15], v[100:101]
	v_pk_mul_f32 v[10:11], v[10:11], v[104:105]
	v_pk_mul_f32 v[6:7], v[6:7], v[112:113]
	s_waitcnt lgkmcnt(0)
	v_pk_mul_f32 v[2:3], v[2:3], v[116:117]
	v_pk_mul_f32 v[0:1], v[0:1], v[114:115]
	v_pk_mul_f32 v[60:61], v[60:61], v[98:99]
	v_pk_mul_f32 v[56:57], v[56:57], v[102:103]
	v_pk_mul_f32 v[52:53], v[52:53], v[110:111]
	v_pk_mul_f32 v[62:63], v[62:63], v[100:101]
	v_pk_mul_f32 v[58:59], v[58:59], v[104:105]
	v_pk_mul_f32 v[54:55], v[54:55], v[112:113]
	v_pk_mul_f32 v[50:51], v[50:51], v[116:117]
	v_pk_mul_f32 v[48:49], v[48:49], v[114:115]
	v_pk_mul_f32 v[44:45], v[44:45], v[98:99]
	v_pk_mul_f32 v[40:41], v[40:41], v[102:103]
	v_pk_mul_f32 v[36:37], v[36:37], v[110:111]
	v_pk_mul_f32 v[46:47], v[46:47], v[100:101]
	v_pk_mul_f32 v[42:43], v[42:43], v[104:105]
	v_pk_mul_f32 v[38:39], v[38:39], v[112:113]
	v_pk_mul_f32 v[34:35], v[34:35], v[116:117]
	v_pk_mul_f32 v[32:33], v[32:33], v[114:115]
	v_pk_mul_f32 v[28:29], v[28:29], v[98:99]
	v_pk_mul_f32 v[24:25], v[24:25], v[102:103]
	v_pk_mul_f32 v[20:21], v[20:21], v[110:111]
	v_pk_mul_f32 v[30:31], v[30:31], v[100:101]
	v_pk_mul_f32 v[26:27], v[26:27], v[104:105]
	v_pk_mul_f32 v[22:23], v[22:23], v[112:113]
	v_pk_mul_f32 v[18:19], v[18:19], v[116:117]
	v_pk_mul_f32 v[16:17], v[16:17], v[114:115]
